# P2 epilogue: both copy_tile loops replaced by straight-line code with 8 LDS reads in flight and counted waits
# speedup vs baseline: 1.0128x; 1.0017x over previous
; DI int tid_() { int t = threadIdx.x; asm volatile("" : "+v"(t)); return t; }
; DI float sigmoidf_(float x) { return 1.f / (1.f + __expf(-x)); }
; DI void lds_sync() { wait_lgkm0(); bar_(); }
; template <class RF>
; DI void copy_tile(const char* tile, int pitch, int rows, int lch, RF dst, int ch0, int ch1) {
;   const int t = tid_();
;   const int total = rows << lch;
;   for (int id = t; id < total; id += NTH) {
;     const int row = id >> lch, ch = id & ((1 << lch) - 1);
;     if (ch >= ch0 && ch < ch1) *(uint4*)(dst(row) + ch * 8) = *(const uint4*)(tile + row * pitch + ch * 16);
;   }
; }
; DI void phase2(const Params& p, char* smem) {
;     ...
;     char* tile = smem + EPI_OFF;
;     bf16_t* base; int ld, c0 = 0, c1 = 32;
;     if (lat) {
;       const size_t tok0 = (size_t)tokTile * 256;
;       if (ft < 3) { base = p.pqkv + tok0 * LDQKV + ft * 256; ld = LDQKV; if (ft == 2) c1 = 20; }
;       else if (ft < 5) { base = p.pf + tok0 * 512 + (ft - 3) * 256; ld = 512; }
;       else { base = p.pg + tok0 * 2048 + (ft - 5) * 256; ld = 2048; }
;     } else {
;       const size_t ct0 = (size_t)(tokTile - 256) * 256;
;       base = p.pckv + ct0 * LDCKV + ft * 256 - 384; ld = LDCKV;
;       if (ft == 1) c0 = 16; else c1 = 20;
;     }
;     if (ft >= 5) stage_half<4, 2, 4, 0>(acc, tile, 528, [](float v) { return sigmoidf_(v); });
;     else stage_half<4, 2, 4, 0>(acc, tile, 528, [](float v) { return v; });
;     lds_sync();
;     copy_tile(tile, 528, 128, 5, [&](int rl) { return base + (size_t)((rl >> 5) * 64 + (rl & 31)) * ld; }, c0, c1);
;     lds_sync();
;     if (ft >= 5) stage_half<4, 2, 4, 1>(acc, tile, 528, [](float v) { return sigmoidf_(v); });
;     else stage_half<4, 2, 4, 1>(acc, tile, 528, [](float v) { return v; });
;     lds_sync();
;     copy_tile(tile, 528, 128, 5, [&](int rl) { return base + (size_t)((rl >> 5) * 64 + 32 + (rl & 31)) * ld; }, c0, c1);
.LBB0_282:
	v_cvt_pk_bf16_f32 v64, v76, v77
	v_cvt_pk_bf16_f32 v65, v78, v79
	s_waitcnt vmcnt(0)
	ds_write_b64 v128, v[64:65] offset:48
	s_waitcnt lgkmcnt(0)
	v_mov_b32_e32 v65, v220
	s_barrier
	s_nop 0
	v_cmp_gt_i32_e32 vcc, s61, v65
	s_and_saveexec_b64 s[12:13], vcc
	s_cbranch_execz .LBB0_287
	v_and_b32_e32 v64, 31, v65
	v_cmp_le_u32_e32 vcc, s41, v64
	v_cmp_gt_u32_e64 s[4:5], s40, v64
	v_lshlrev_b32_e32 v184, 4, v64
	s_and_b64 s[4:5], vcc, s[4:5]
	s_and_saveexec_b64 s[38:39], s[4:5]
	s_cbranch_execz .Lcp0_done
	v_lshrrev_b32_e32 v70, 5, v65
	v_mad_u32_u24 v68, v70, s60, v184
	v_add_u32_e32 v68, 0x10000, v68
	ds_read_b128 v[128:131], v68
	ds_read_b128 v[132:135], v68 offset:8448
	ds_read_b128 v[136:139], v68 offset:16896
	ds_read_b128 v[140:143], v68 offset:25344
	ds_read_b128 v[144:147], v68 offset:33792
	ds_read_b128 v[148:151], v68 offset:42240
	ds_read_b128 v[152:155], v68 offset:50688
	ds_read_b128 v[156:159], v68 offset:59136
	v_lshl_add_u64 v[66:67], s[6:7], 0, v[184:185]
	v_mad_u64_u32 v[72:73], s[36:37], s8, v70, 0
	v_lshl_add_u64 v[66:67], v[72:73], 1, v[66:67]
	s_waitcnt lgkmcnt(7)
	global_store_dwordx4 v[66:67], v[128:131], off
	s_waitcnt lgkmcnt(6)
	s_mul_i32 s36, s8, 32
	s_mov_b32 s37, 0
	v_lshl_add_u64 v[72:73], v[66:67], 0, s[36:37]
	global_store_dwordx4 v[72:73], v[132:135], off
	s_waitcnt lgkmcnt(5)
	s_mul_i32 s36, s8, 128
	s_mov_b32 s37, 0
	v_lshl_add_u64 v[72:73], v[66:67], 0, s[36:37]
	global_store_dwordx4 v[72:73], v[136:139], off
	s_waitcnt lgkmcnt(4)
	s_mul_i32 s36, s8, 160
	s_mov_b32 s37, 0
	v_lshl_add_u64 v[72:73], v[66:67], 0, s[36:37]
	global_store_dwordx4 v[72:73], v[140:143], off
	s_waitcnt lgkmcnt(3)
	s_mul_i32 s36, s8, 256
	s_mov_b32 s37, 0
	v_lshl_add_u64 v[72:73], v[66:67], 0, s[36:37]
	global_store_dwordx4 v[72:73], v[144:147], off
	s_waitcnt lgkmcnt(2)
	s_mul_i32 s36, s8, 288
	s_mov_b32 s37, 0
	v_lshl_add_u64 v[72:73], v[66:67], 0, s[36:37]
	global_store_dwordx4 v[72:73], v[148:151], off
	s_waitcnt lgkmcnt(1)
	s_mul_i32 s36, s8, 384
	s_mov_b32 s37, 0
	v_lshl_add_u64 v[72:73], v[66:67], 0, s[36:37]
	global_store_dwordx4 v[72:73], v[152:155], off
	s_waitcnt lgkmcnt(0)
	s_mul_i32 s36, s8, 416
	s_mov_b32 s37, 0
	v_lshl_add_u64 v[72:73], v[66:67], 0, s[36:37]
	global_store_dwordx4 v[72:73], v[156:159], off
.Lcp0_done:
	s_or_b64 exec, exec, s[38:39]
.LBB0_287:
	s_or_b64 exec, exec, s[12:13]
	s_waitcnt lgkmcnt(0)
	s_mov_b64 s[4:5], -1
	s_and_b64 vcc, exec, s[10:11]
	s_barrier
	s_cbranch_vccnz .Lp2_id1
	v_mul_f32_e32 v0, 0xbfb8aa3b, v0
	v_mul_f32_e32 v1, 0xbfb8aa3b, v1
	v_mul_f32_e32 v2, 0xbfb8aa3b, v2
	v_mul_f32_e32 v3, 0xbfb8aa3b, v3
	v_mul_f32_e32 v4, 0xbfb8aa3b, v4
	v_mul_f32_e32 v5, 0xbfb8aa3b, v5
	v_mul_f32_e32 v6, 0xbfb8aa3b, v6
	v_mul_f32_e32 v7, 0xbfb8aa3b, v7
	v_exp_f32_e32 v0, v0
	v_exp_f32_e32 v1, v1
	v_exp_f32_e32 v2, v2
	v_exp_f32_e32 v3, v3
	v_exp_f32_e32 v4, v4
	v_exp_f32_e32 v5, v5
	v_exp_f32_e32 v6, v6
	v_exp_f32_e32 v7, v7
	v_add_f32_e32 v0, 1.0, v0
	v_add_f32_e32 v1, 1.0, v1
	v_add_f32_e32 v2, 1.0, v2
	v_add_f32_e32 v3, 1.0, v3
	v_add_f32_e32 v4, 1.0, v4
	v_add_f32_e32 v5, 1.0, v5
	v_add_f32_e32 v6, 1.0, v6
	v_add_f32_e32 v7, 1.0, v7
	v_rcp_f32_e32 v0, v0
	v_rcp_f32_e32 v1, v1
	v_rcp_f32_e32 v2, v2
	v_rcp_f32_e32 v3, v3
	v_rcp_f32_e32 v4, v4
	v_rcp_f32_e32 v5, v5
	v_rcp_f32_e32 v6, v6
	v_rcp_f32_e32 v7, v7
	v_mul_f32_e32 v8, 0xbfb8aa3b, v8
	v_mul_f32_e32 v9, 0xbfb8aa3b, v9
	v_mul_f32_e32 v10, 0xbfb8aa3b, v10
	v_mul_f32_e32 v11, 0xbfb8aa3b, v11
	v_mul_f32_e32 v12, 0xbfb8aa3b, v12
	v_mul_f32_e32 v13, 0xbfb8aa3b, v13
	v_mul_f32_e32 v14, 0xbfb8aa3b, v14
	v_mul_f32_e32 v15, 0xbfb8aa3b, v15
	v_exp_f32_e32 v8, v8
	v_exp_f32_e32 v9, v9
	v_exp_f32_e32 v10, v10
	v_exp_f32_e32 v11, v11
	v_exp_f32_e32 v12, v12
	v_exp_f32_e32 v13, v13
	v_exp_f32_e32 v14, v14
	v_exp_f32_e32 v15, v15
	v_add_f32_e32 v8, 1.0, v8
	v_add_f32_e32 v9, 1.0, v9
	v_add_f32_e32 v10, 1.0, v10
	v_add_f32_e32 v11, 1.0, v11
	v_add_f32_e32 v12, 1.0, v12
	v_add_f32_e32 v13, 1.0, v13
	v_add_f32_e32 v14, 1.0, v14
	v_add_f32_e32 v15, 1.0, v15
	v_rcp_f32_e32 v8, v8
	v_rcp_f32_e32 v9, v9
	v_rcp_f32_e32 v10, v10
	v_rcp_f32_e32 v11, v11
	v_rcp_f32_e32 v12, v12
	v_rcp_f32_e32 v13, v13
	v_rcp_f32_e32 v14, v14
	v_rcp_f32_e32 v15, v15
	v_mul_f32_e32 v16, 0xbfb8aa3b, v16
	v_mul_f32_e32 v17, 0xbfb8aa3b, v17
	v_mul_f32_e32 v18, 0xbfb8aa3b, v18
	v_mul_f32_e32 v19, 0xbfb8aa3b, v19
	v_mul_f32_e32 v20, 0xbfb8aa3b, v20
	v_mul_f32_e32 v21, 0xbfb8aa3b, v21
	v_mul_f32_e32 v22, 0xbfb8aa3b, v22
	v_mul_f32_e32 v23, 0xbfb8aa3b, v23
	v_exp_f32_e32 v16, v16
	v_exp_f32_e32 v17, v17
	v_exp_f32_e32 v18, v18
	v_exp_f32_e32 v19, v19
	v_exp_f32_e32 v20, v20
	v_exp_f32_e32 v21, v21
	v_exp_f32_e32 v22, v22
	v_exp_f32_e32 v23, v23
	v_add_f32_e32 v16, 1.0, v16
	v_add_f32_e32 v17, 1.0, v17
	v_add_f32_e32 v18, 1.0, v18
	v_add_f32_e32 v19, 1.0, v19
; DI float sigmoidf_(float x) { return 1.f / (1.f + __expf(-x)); }
; DI void phase2(const Params& p, char* smem) {
;     ...
;     if (ft >= 5) stage_half<4, 2, 4, 1>(acc, tile, 528, [](float v) { return sigmoidf_(v); });
;     else stage_half<4, 2, 4, 1>(acc, tile, 528, [](float v) { return v; });
	v_add_f32_e32 v20, 1.0, v20
	v_add_f32_e32 v21, 1.0, v21
	v_add_f32_e32 v22, 1.0, v22
	v_add_f32_e32 v23, 1.0, v23
	v_rcp_f32_e32 v16, v16
	v_rcp_f32_e32 v17, v17
	v_rcp_f32_e32 v18, v18
	v_rcp_f32_e32 v19, v19
	v_rcp_f32_e32 v20, v20
	v_rcp_f32_e32 v21, v21
	v_rcp_f32_e32 v22, v22
	v_rcp_f32_e32 v23, v23
	v_mul_f32_e32 v24, 0xbfb8aa3b, v24
	v_mul_f32_e32 v25, 0xbfb8aa3b, v25
	v_mul_f32_e32 v26, 0xbfb8aa3b, v26
	v_mul_f32_e32 v27, 0xbfb8aa3b, v27
	v_mul_f32_e32 v28, 0xbfb8aa3b, v28
	v_mul_f32_e32 v29, 0xbfb8aa3b, v29
	v_mul_f32_e32 v30, 0xbfb8aa3b, v30
	v_mul_f32_e32 v31, 0xbfb8aa3b, v31
	v_exp_f32_e32 v24, v24
	v_exp_f32_e32 v25, v25
	v_exp_f32_e32 v26, v26
	v_exp_f32_e32 v27, v27
	v_exp_f32_e32 v28, v28
	v_exp_f32_e32 v29, v29
	v_exp_f32_e32 v30, v30
	v_exp_f32_e32 v31, v31
	v_add_f32_e32 v24, 1.0, v24
	v_add_f32_e32 v25, 1.0, v25
	v_add_f32_e32 v26, 1.0, v26
	v_add_f32_e32 v27, 1.0, v27
	v_add_f32_e32 v28, 1.0, v28
	v_add_f32_e32 v29, 1.0, v29
	v_add_f32_e32 v30, 1.0, v30
	v_add_f32_e32 v31, 1.0, v31
	v_rcp_f32_e32 v24, v24
	v_rcp_f32_e32 v25, v25
	v_rcp_f32_e32 v26, v26
	v_rcp_f32_e32 v27, v27
	v_rcp_f32_e32 v28, v28
	v_rcp_f32_e32 v29, v29
	v_rcp_f32_e32 v30, v30
	v_rcp_f32_e32 v31, v31
	v_mul_f32_e32 v32, 0xbfb8aa3b, v32
	v_mul_f32_e32 v33, 0xbfb8aa3b, v33
	v_mul_f32_e32 v34, 0xbfb8aa3b, v34
	v_mul_f32_e32 v35, 0xbfb8aa3b, v35
	v_mul_f32_e32 v36, 0xbfb8aa3b, v36
	v_mul_f32_e32 v37, 0xbfb8aa3b, v37
	v_mul_f32_e32 v38, 0xbfb8aa3b, v38
	v_mul_f32_e32 v39, 0xbfb8aa3b, v39
	v_exp_f32_e32 v32, v32
	v_exp_f32_e32 v33, v33
	v_exp_f32_e32 v34, v34
	v_exp_f32_e32 v35, v35
	v_exp_f32_e32 v36, v36
	v_exp_f32_e32 v37, v37
	v_exp_f32_e32 v38, v38
	v_exp_f32_e32 v39, v39
	v_add_f32_e32 v32, 1.0, v32
	v_add_f32_e32 v33, 1.0, v33
	v_add_f32_e32 v34, 1.0, v34
	v_add_f32_e32 v35, 1.0, v35
	v_add_f32_e32 v36, 1.0, v36
	v_add_f32_e32 v37, 1.0, v37
	v_add_f32_e32 v38, 1.0, v38
	v_add_f32_e32 v39, 1.0, v39
	v_rcp_f32_e32 v32, v32
	v_rcp_f32_e32 v33, v33
	v_rcp_f32_e32 v34, v34
	v_rcp_f32_e32 v35, v35
	v_rcp_f32_e32 v36, v36
	v_rcp_f32_e32 v37, v37
	v_rcp_f32_e32 v38, v38
	v_rcp_f32_e32 v39, v39
	v_mul_f32_e32 v40, 0xbfb8aa3b, v40
	v_mul_f32_e32 v41, 0xbfb8aa3b, v41
	v_mul_f32_e32 v42, 0xbfb8aa3b, v42
	v_mul_f32_e32 v43, 0xbfb8aa3b, v43
	v_mul_f32_e32 v44, 0xbfb8aa3b, v44
	v_mul_f32_e32 v45, 0xbfb8aa3b, v45
	v_mul_f32_e32 v46, 0xbfb8aa3b, v46
	v_mul_f32_e32 v47, 0xbfb8aa3b, v47
	v_exp_f32_e32 v40, v40
	v_exp_f32_e32 v41, v41
	v_exp_f32_e32 v42, v42
	v_exp_f32_e32 v43, v43
	v_exp_f32_e32 v44, v44
	v_exp_f32_e32 v45, v45
	v_exp_f32_e32 v46, v46
	v_exp_f32_e32 v47, v47
	v_add_f32_e32 v40, 1.0, v40
	v_add_f32_e32 v41, 1.0, v41
	v_add_f32_e32 v42, 1.0, v42
	v_add_f32_e32 v43, 1.0, v43
	v_add_f32_e32 v44, 1.0, v44
	v_add_f32_e32 v45, 1.0, v45
	v_add_f32_e32 v46, 1.0, v46
	v_add_f32_e32 v47, 1.0, v47
	v_rcp_f32_e32 v40, v40
	v_rcp_f32_e32 v41, v41
	v_rcp_f32_e32 v42, v42
	v_rcp_f32_e32 v43, v43
	v_rcp_f32_e32 v44, v44
	v_rcp_f32_e32 v45, v45
	v_rcp_f32_e32 v46, v46
	v_rcp_f32_e32 v47, v47
	v_mul_f32_e32 v48, 0xbfb8aa3b, v48
	v_mul_f32_e32 v49, 0xbfb8aa3b, v49
	v_mul_f32_e32 v50, 0xbfb8aa3b, v50
	v_mul_f32_e32 v51, 0xbfb8aa3b, v51
	v_mul_f32_e32 v52, 0xbfb8aa3b, v52
	v_mul_f32_e32 v53, 0xbfb8aa3b, v53
	v_mul_f32_e32 v54, 0xbfb8aa3b, v54
	v_mul_f32_e32 v55, 0xbfb8aa3b, v55
	v_exp_f32_e32 v48, v48
	v_exp_f32_e32 v49, v49
	v_exp_f32_e32 v50, v50
	v_exp_f32_e32 v51, v51
	v_exp_f32_e32 v52, v52
	v_exp_f32_e32 v53, v53
	v_exp_f32_e32 v54, v54
	v_exp_f32_e32 v55, v55
	v_add_f32_e32 v48, 1.0, v48
	v_add_f32_e32 v49, 1.0, v49
	v_add_f32_e32 v50, 1.0, v50
	v_add_f32_e32 v51, 1.0, v51
	v_add_f32_e32 v52, 1.0, v52
	v_add_f32_e32 v53, 1.0, v53
	v_add_f32_e32 v54, 1.0, v54
	v_add_f32_e32 v55, 1.0, v55
	v_rcp_f32_e32 v48, v48
	v_rcp_f32_e32 v49, v49
	v_rcp_f32_e32 v50, v50
	v_rcp_f32_e32 v51, v51
	v_rcp_f32_e32 v52, v52
	v_rcp_f32_e32 v53, v53
	v_rcp_f32_e32 v54, v54
	v_rcp_f32_e32 v55, v55
	v_mul_f32_e32 v56, 0xbfb8aa3b, v56
	v_mul_f32_e32 v57, 0xbfb8aa3b, v57
	v_mul_f32_e32 v58, 0xbfb8aa3b, v58
	v_mul_f32_e32 v59, 0xbfb8aa3b, v59
	v_mul_f32_e32 v60, 0xbfb8aa3b, v60
	v_mul_f32_e32 v61, 0xbfb8aa3b, v61
	v_mul_f32_e32 v62, 0xbfb8aa3b, v62
	v_mul_f32_e32 v63, 0xbfb8aa3b, v63
	v_exp_f32_e32 v56, v56
	v_exp_f32_e32 v57, v57
	v_exp_f32_e32 v58, v58
	v_exp_f32_e32 v59, v59
	v_exp_f32_e32 v60, v60
	v_exp_f32_e32 v61, v61
	v_exp_f32_e32 v62, v62
	v_exp_f32_e32 v63, v63
	v_add_f32_e32 v56, 1.0, v56
	v_add_f32_e32 v57, 1.0, v57
	v_add_f32_e32 v58, 1.0, v58
	v_add_f32_e32 v59, 1.0, v59
	v_add_f32_e32 v60, 1.0, v60
	v_add_f32_e32 v61, 1.0, v61
	v_add_f32_e32 v62, 1.0, v62
	v_add_f32_e32 v63, 1.0, v63
	v_rcp_f32_e32 v56, v56
	v_rcp_f32_e32 v57, v57
	v_rcp_f32_e32 v58, v58
	v_rcp_f32_e32 v59, v59
	v_rcp_f32_e32 v60, v60
	v_rcp_f32_e32 v61, v61
	v_rcp_f32_e32 v62, v62
	v_rcp_f32_e32 v63, v63

; DI int tid_() { int t = threadIdx.x; asm volatile("" : "+v"(t)); return t; }
; DI void lds_sync() { wait_lgkm0(); bar_(); }
; template <class RF>
; DI void copy_tile(const char* tile, int pitch, int rows, int lch, RF dst, int ch0, int ch1) {
;   const int t = tid_();
;   const int total = rows << lch;
;   for (int id = t; id < total; id += NTH) {
;     const int row = id >> lch, ch = id & ((1 << lch) - 1);
;     if (ch >= ch0 && ch < ch1) *(uint4*)(dst(row) + ch * 8) = *(const uint4*)(tile + row * pitch + ch * 16);
;   }
; }
; DI void phase2(const Params& p, char* smem) {
;     ...
;     else stage_half<4, 2, 4, 1>(acc, tile, 528, [](float v) { return v; });
;     lds_sync();
;     copy_tile(tile, 528, 128, 5, [&](int rl) { return base + (size_t)((rl >> 5) * 64 + 32 + (rl & 31)) * ld; }, c0, c1);
.LBB0_291:
	v_cvt_pk_bf16_f32 v0, v12, v13
	v_cvt_pk_bf16_f32 v1, v14, v15
	ds_write_b64 v64, v[0:1] offset:48
	s_waitcnt lgkmcnt(0)
	v_mov_b32_e32 v1, v220
	s_barrier
	s_nop 0
	v_cmp_gt_i32_e32 vcc, s61, v1
	s_and_saveexec_b64 s[10:11], vcc
	s_cbranch_execz .LBB0_200
	v_and_b32_e32 v0, 31, v1
	v_cmp_le_u32_e32 vcc, s41, v0
	v_cmp_gt_u32_e64 s[4:5], s40, v0
	v_lshlrev_b32_e32 v184, 4, v0
	s_and_b64 s[4:5], vcc, s[4:5]
	s_and_saveexec_b64 s[12:13], s[4:5]
	s_cbranch_execz .Lcp1_done
	v_lshrrev_b32_e32 v6, 5, v1
	v_mad_u32_u24 v4, v6, s60, v184
	v_add_u32_e32 v4, 0x10000, v4
	ds_read_b128 v[128:131], v4
	ds_read_b128 v[132:135], v4 offset:8448
	ds_read_b128 v[136:139], v4 offset:16896
	ds_read_b128 v[140:143], v4 offset:25344
	ds_read_b128 v[144:147], v4 offset:33792
	ds_read_b128 v[148:151], v4 offset:42240
	ds_read_b128 v[152:155], v4 offset:50688
	ds_read_b128 v[156:159], v4 offset:59136
	v_lshl_add_u64 v[2:3], s[6:7], 0, v[184:185]
	v_or_b32_e32 v6, 32, v6
	v_mad_u64_u32 v[8:9], s[36:37], s8, v6, 0
	v_lshl_add_u64 v[2:3], v[8:9], 1, v[2:3]
	s_waitcnt lgkmcnt(7)
	global_store_dwordx4 v[2:3], v[128:131], off
	s_waitcnt lgkmcnt(6)
	s_mul_i32 s36, s8, 32
	s_mov_b32 s37, 0
	v_lshl_add_u64 v[8:9], v[2:3], 0, s[36:37]
	global_store_dwordx4 v[8:9], v[132:135], off
	s_waitcnt lgkmcnt(5)
	s_mul_i32 s36, s8, 128
	s_mov_b32 s37, 0
	v_lshl_add_u64 v[8:9], v[2:3], 0, s[36:37]
	global_store_dwordx4 v[8:9], v[136:139], off
	s_waitcnt lgkmcnt(4)
	s_mul_i32 s36, s8, 160
	s_mov_b32 s37, 0
	v_lshl_add_u64 v[8:9], v[2:3], 0, s[36:37]
	global_store_dwordx4 v[8:9], v[140:143], off
	s_waitcnt lgkmcnt(3)
	s_mul_i32 s36, s8, 256
	s_mov_b32 s37, 0
	v_lshl_add_u64 v[8:9], v[2:3], 0, s[36:37]
	global_store_dwordx4 v[8:9], v[144:147], off
	s_waitcnt lgkmcnt(2)
	s_mul_i32 s36, s8, 288
	s_mov_b32 s37, 0
	v_lshl_add_u64 v[8:9], v[2:3], 0, s[36:37]
	global_store_dwordx4 v[8:9], v[148:151], off
	s_waitcnt lgkmcnt(1)
	s_mul_i32 s36, s8, 384
	s_mov_b32 s37, 0
	v_lshl_add_u64 v[8:9], v[2:3], 0, s[36:37]
	global_store_dwordx4 v[8:9], v[152:155], off
	s_waitcnt lgkmcnt(0)
	s_mul_i32 s36, s8, 416
	s_mov_b32 s37, 0
	v_lshl_add_u64 v[8:9], v[2:3], 0, s[36:37]
	global_store_dwordx4 v[8:9], v[156:159], off
